# attention: row-max as a v_max3 tree (16 ops, 4 levels, instead of 23 serial), K-fragment ds_reads issued before the next-tile global loads at the loop head
# speedup vs baseline: 1.0087x; 1.0006x over previous
; #define LAS __attribute__((address_space(3)))
; __device__ __forceinline__ int crow(int r, int hi) { return (r & 3) + 8 * (r >> 2) + 4 * hi; }
; #define MFMA32(a, b, c) __builtin_amdgcn_mfma_f32_32x32x16_bf16((a), (b), (c), 0, 0, 0)
; __device__ __forceinline__ void unit(LAS unsigned char* lds, const Tensors& T, int h, int qrow0, int nact, bool sample, int limbase, int kv0, int kvnew, int nt) {
;     ...
;     for (int t = 0; t < nt; ++t) {
;         const int buf = t & 1;
;         if (t + 1 < nt) ATT_ISSUE(t + 1);
;         if (active && t <= lim) {
;             const LAS unsigned char* kp = lds + OFF_K + buf * KBUF + r32 * KP + hi * 16;
;             f32x16 p0, p1;
; #pragma unroll
;             for (int r = 0; r < 16; ++r) { p0[r] = 0.f; p1[r] = 0.f; }
;             { bf16x8 kf[4][2];
; #pragma unroll
;               for (int i = 0; i < 4; ++i) { kf[i][0] = *(const LAS bf16x8*)(kp + i * 32); kf[i][1] = *(const LAS bf16x8*)(kp + 32 * KP + i * 32); }
;               __builtin_amdgcn_sched_barrier(0);
; #pragma unroll
;               for (int i = 0; i < 12; ++i) {
;                   p0 = MFMA32(kf[i & 3][0], qf[i], p0); p1 = MFMA32(kf[i & 3][1], qf[i], p1);
;                   if (i + 4 < 12) { kf[i & 3][0] = *(const LAS bf16x8*)(kp + (i + 4) * 32); kf[i & 3][1] = *(const LAS bf16x8*)(kp + 32 * KP + (i + 4) * 32); }
;                   __builtin_amdgcn_sched_barrier(0);
;               } }
;             float rm = fmaxf(p0[0], p1[0]);
; #pragma unroll
;             for (int r = 1; r < 16; ++r) rm = fmaxf(rm, fmaxf(p0[r], p1[r]));
;             { const auto rr = __builtin_amdgcn_permlane32_swap(__float_as_uint(rm), __float_as_uint(rm), false, false);
;               rm = fmaxf(__uint_as_float(rr[0]), __uint_as_float(rr[1])); }
;             const bool need = rm > mrun + 8.0f;
;             if (__builtin_amdgcn_ballot_w64(need) != 0ull) {
;                 const float mn = need ? rm : mrun; const float alpha = __builtin_amdgcn_exp2f(mrun - mn); mrun = mn; lrun *= alpha;
;                 if (hi == 0) scr[r32] = alpha;
;                 asm volatile("s_waitcnt lgkmcnt(0)" ::: "memory");
; #pragma unroll
;                 for (int r = 0; r < 16; ++r) { const float f = scr[crow(r, hi)];
; #pragma unroll
;                     for (int d = 0; d < 4; ++d) o[d][r] *= f; }
;                 asm volatile("s_waitcnt lgkmcnt(0)" ::: "memory");
;             }
.Lat_prio:
.LBB0_904:
	s_and_b32 s16, s9, 1
	s_cmp_gt_i32 s9, s10
	s_cselect_b64 s[0:1], -1, 0
	s_or_b64 s[0:1], s[22:23], s[0:1]
	s_and_b64 vcc, exec, s[0:1]
	s_cbranch_vccnz .LBB0_909
	s_mul_i32 s0, s16, 0x6400
	v_add_u32_e32 v222, s0, v221
	ds_read_b128 v[64:67], v222
	ds_read_b128 v[224:227], v222 offset:32
	ds_read_b128 v[68:71], v222 offset:12800
	ds_read_b128 v[228:231], v222 offset:12832
	ds_read_b128 v[232:235], v222 offset:64
	ds_read_b128 v[236:239], v222 offset:96
	ds_read_b128 v[240:243], v222 offset:12864
	ds_read_b128 v[244:247], v222 offset:12896
	global_load_dwordx4 v[160:163], v[198:199], off
	global_load_dwordx4 v[156:159], v[194:195], off
	global_load_dwordx4 v[152:155], v[192:193], off
	global_load_dwordx4 v[148:151], v[204:205], off
	global_load_dwordx4 v[144:147], v[202:203], off
	s_waitcnt lgkmcnt(7)
	v_mfma_f32_32x32x16_bf16 v[80:95], v[64:67], v[140:143], 0
	ds_read_b128 v[248:251], v222 offset:128
	ds_read_b128 v[166:169], v222 offset:12928
	s_waitcnt lgkmcnt(7)
	v_mfma_f32_32x32x16_bf16 v[64:79], v[68:71], v[140:143], 0
	v_mfma_f32_32x32x16_bf16 v[80:95], v[224:227], v[136:139], v[80:95]
	s_waitcnt lgkmcnt(6)
	v_mfma_f32_32x32x16_bf16 v[64:79], v[228:231], v[136:139], v[64:79]
	ds_read_b128 v[224:227], v222 offset:160
	ds_read_b128 v[228:231], v222 offset:12960
	s_waitcnt lgkmcnt(7)
	v_mfma_f32_32x32x16_bf16 v[80:95], v[232:235], v[132:135], v[80:95]
	s_waitcnt lgkmcnt(5)
	v_mfma_f32_32x32x16_bf16 v[64:79], v[240:243], v[132:135], v[64:79]
	ds_read_b128 v[232:235], v222 offset:192
	ds_read_b128 v[240:243], v222 offset:12992
	v_mfma_f32_32x32x16_bf16 v[80:95], v[236:239], v[128:131], v[80:95]
	s_waitcnt lgkmcnt(6)
	v_mfma_f32_32x32x16_bf16 v[64:79], v[244:247], v[128:131], v[64:79]
	ds_read_b128 v[236:239], v222 offset:224
	ds_read_b128 v[244:247], v222 offset:13024
	s_waitcnt lgkmcnt(7)
	v_mfma_f32_32x32x16_bf16 v[80:95], v[248:251], v[124:127], v[80:95]
	s_waitcnt lgkmcnt(6)
	v_mfma_f32_32x32x16_bf16 v[64:79], v[166:169], v[124:127], v[64:79]
	ds_read_b128 v[166:169], v222 offset:256
	ds_read_b128 v[248:251], v222 offset:13056
	s_waitcnt lgkmcnt(7)
	v_mfma_f32_32x32x16_bf16 v[80:95], v[224:227], v[120:123], v[80:95]
	s_waitcnt lgkmcnt(6)
	v_mfma_f32_32x32x16_bf16 v[64:79], v[228:231], v[120:123], v[64:79]
	ds_read_b128 v[224:227], v222 offset:288
	ds_read_b128 v[228:231], v222 offset:13088
	s_waitcnt lgkmcnt(7)
	v_mfma_f32_32x32x16_bf16 v[80:95], v[232:235], v[116:119], v[80:95]
	s_waitcnt lgkmcnt(6)
	v_mfma_f32_32x32x16_bf16 v[64:79], v[240:243], v[116:119], v[64:79]
	ds_read_b128 v[232:235], v222 offset:320
	ds_read_b128 v[240:243], v222 offset:13120
	s_waitcnt lgkmcnt(7)
	v_mfma_f32_32x32x16_bf16 v[80:95], v[236:239], v[112:115], v[80:95]
	s_waitcnt lgkmcnt(6)
	v_mfma_f32_32x32x16_bf16 v[64:79], v[244:247], v[112:115], v[64:79]
	ds_read_b128 v[236:239], v222 offset:352
	ds_read_b128 v[244:247], v222 offset:13152
	s_waitcnt lgkmcnt(7)
	v_mfma_f32_32x32x16_bf16 v[80:95], v[166:169], v[108:111], v[80:95]
	s_waitcnt lgkmcnt(6)
	v_mfma_f32_32x32x16_bf16 v[64:79], v[248:251], v[108:111], v[64:79]
	s_waitcnt lgkmcnt(5)
	v_mfma_f32_32x32x16_bf16 v[80:95], v[224:227], v[104:107], v[80:95]
	s_waitcnt lgkmcnt(4)
	v_mfma_f32_32x32x16_bf16 v[64:79], v[228:231], v[104:107], v[64:79]
	s_waitcnt lgkmcnt(3)
	v_mfma_f32_32x32x16_bf16 v[80:95], v[232:235], v[100:103], v[80:95]
	s_waitcnt lgkmcnt(2)
	v_mfma_f32_32x32x16_bf16 v[64:79], v[240:243], v[100:103], v[64:79]
	s_waitcnt lgkmcnt(1)
	v_mfma_f32_32x32x16_bf16 v[80:95], v[236:239], v[96:99], v[80:95]
	s_waitcnt lgkmcnt(0)
	v_mfma_f32_32x32x16_bf16 v[64:79], v[244:247], v[96:99], v[64:79]
	s_nop 11
	v_max3_f32 v224, v64, v65, v66
	v_max3_f32 v225, v67, v68, v69
	v_max3_f32 v226, v70, v71, v72
	v_max3_f32 v227, v73, v74, v75
	v_max3_f32 v228, v76, v77, v78
	v_max3_f32 v229, v79, v80, v81
	v_max3_f32 v230, v82, v83, v84
	v_max3_f32 v231, v85, v86, v87
	v_max3_f32 v232, v88, v89, v90
	v_max3_f32 v233, v91, v92, v93
	v_max3_f32 v224, v224, v225, v226
	v_max3_f32 v227, v227, v228, v229
	v_max3_f32 v230, v230, v231, v232
	v_max3_f32 v233, v233, v94, v95
	v_max3_f32 v224, v224, v227, v230
	v_max_f32_e32 v166, v224, v233
	v_mov_b32_e32 v167, v166
	s_nop 1
	v_permlane32_swap_b32_e32 v166, v167
	v_max_f32_e32 v222, v166, v167
	v_add_f32_e32 v166, 0x41000000, v223
	v_cmp_gt_f32_e32 vcc, v222, v166
	s_cbranch_vccz .LBB0_910
	s_nop 0
	v_cndmask_b32_e32 v222, v223, v222, vcc
	v_sub_f32_e32 v166, v223, v222
	v_exp_f32_e32 v223, v166
	s_and_saveexec_b64 s[0:1], s[38:39]
	ds_write_b32 v189, v223
	s_or_b64 exec, exec, s[0:1]
	v_mul_f32_e32 v191, v191, v223
	s_waitcnt lgkmcnt(0)
	v_add_u32_e32 v223, s12, v186
	ds_read_b128 v[166:169], v223
	ds_read_b128 v[224:227], v223 offset:32
	ds_read_b128 v[228:231], v223 offset:64
	ds_read_b128 v[232:235], v223 offset:96
	s_waitcnt lgkmcnt(0)
	s_waitcnt lgkmcnt(3)
	v_pk_mul_f32 v[2:3], v[2:3], v[168:169]
	s_waitcnt lgkmcnt(2)
	v_pk_mul_f32 v[4:5], v[4:5], v[224:225]
	s_waitcnt lgkmcnt(1)
	v_pk_mul_f32 v[8:9], v[8:9], v[228:229]
	s_waitcnt lgkmcnt(0)
	v_pk_mul_f32 v[12:13], v[12:13], v[232:233]
	v_pk_mul_f32 v[14:15], v[14:15], v[234:235]
	v_pk_mul_f32 v[10:11], v[10:11], v[230:231]
	v_pk_mul_f32 v[6:7], v[6:7], v[226:227]
	v_pk_mul_f32 v[0:1], v[0:1], v[166:167]
	v_pk_mul_f32 v[60:61], v[60:61], v[232:233]
	v_pk_mul_f32 v[56:57], v[56:57], v[228:229]
	v_pk_mul_f32 v[52:53], v[52:53], v[224:225]
	v_pk_mul_f32 v[62:63], v[62:63], v[234:235]
	v_pk_mul_f32 v[58:59], v[58:59], v[230:231]
	v_pk_mul_f32 v[54:55], v[54:55], v[226:227]
	v_pk_mul_f32 v[50:51], v[50:51], v[168:169]
	v_pk_mul_f32 v[48:49], v[48:49], v[166:167]
	v_pk_mul_f32 v[44:45], v[44:45], v[232:233]
	v_pk_mul_f32 v[40:41], v[40:41], v[228:229]
	v_pk_mul_f32 v[36:37], v[36:37], v[224:225]
	v_pk_mul_f32 v[46:47], v[46:47], v[234:235]
	v_pk_mul_f32 v[42:43], v[42:43], v[230:231]
	v_pk_mul_f32 v[38:39], v[38:39], v[226:227]
	v_pk_mul_f32 v[34:35], v[34:35], v[168:169]
	v_pk_mul_f32 v[32:33], v[32:33], v[166:167]
	v_pk_mul_f32 v[28:29], v[28:29], v[232:233]
	v_pk_mul_f32 v[24:25], v[24:25], v[228:229]
	v_pk_mul_f32 v[20:21], v[20:21], v[224:225]
	v_pk_mul_f32 v[30:31], v[30:31], v[234:235]
	v_pk_mul_f32 v[26:27], v[26:27], v[230:231]
	v_pk_mul_f32 v[22:23], v[22:23], v[226:227]
	v_pk_mul_f32 v[18:19], v[18:19], v[168:169]
	v_pk_mul_f32 v[16:17], v[16:17], v[166:167]
	s_branch .LBB0_911
.LBB0_909:
	global_load_dwordx4 v[160:163], v[198:199], off
	global_load_dwordx4 v[156:159], v[194:195], off
	global_load_dwordx4 v[152:155], v[192:193], off
	global_load_dwordx4 v[148:151], v[204:205], off
	global_load_dwordx4 v[144:147], v[202:203], off
	v_mov_b32_e32 v222, v223
	s_branch .LBB0_912
